# RWKV readout row loop rewritten: per-lane parameters hoisted, the seven row loads issued together and the next row prefetched while the current row is reduced
# speedup vs baseline: 1.1396x; 1.0047x over previous
; DI float bflo(unsigned u) { return __uint_as_float(u << 16); }
; DI void readout_row(const Params& p, int l, int r) {
;   LAUNDER_IDS
;   const int lane = tid__ & 63;
;   const u16* sc = (const u16*)(p.ws + OFF_R3);
;   const size_t AS = (size_t)NT * 256;
;   const size_t o = (size_t)r * 256 + lane * 4;
;   const u16* Yf = (const u16*)(p.ws + OFF_R2);
;   const uint2 yf = *(const uint2*)(Yf + o), yb = *(const uint2*)(Yf + AS + o);
;   const uint2 ur = *(const uint2*)(sc + SA_R * AS + o), uv = *(const uint2*)(sc + SA_V * AS + o);
;   const uint2 kf = *(const uint2*)(sc + SA_KDF * AS + o), kb = *(const uint2*)(sc + SA_KDB * AS + o), ug = *(const uint2*)(sc + SA_G * AS + o);
;   float y[4] = {bflo(yf.x) + bflo(yb.x), bfhi(yf.x) + bfhi(yb.x), bflo(yf.y) + bflo(yb.y), bfhi(yf.y) + bfhi(yb.y)};
;   const float rr[4] = {bflo(ur.x), bfhi(ur.x), bflo(ur.y), bfhi(ur.y)};
;   const float vv[4] = {bflo(uv.x), bfhi(uv.x), bflo(uv.y), bfhi(uv.y)};
;   const float km[4] = {0.5f * (bflo(kf.x) + bflo(kb.x)), 0.5f * (bfhi(kf.x) + bfhi(kb.x)), 0.5f * (bflo(kf.y) + bflo(kb.y)), 0.5f * (bfhi(kf.y) + bfhi(kb.y))};
;   const float gg[4] = {bflo(ug.x), bfhi(ug.x), bflo(ug.y), bfhi(ug.y)};
;   const float4 rk4 = *(const float4*)(p.in[I_RK] + l * 256 + lane * 4);
;   const float4 lw4 = *(const float4*)(p.in[I_LNW] + l * 256 + lane * 4);
;   const float4 lb4 = *(const float4*)(p.in[I_LNB] + l * 256 + lane * 4);
;   const float rk[4] = {rk4.x, rk4.y, rk4.z, rk4.w}, lw[4] = {lw4.x, lw4.y, lw4.z, lw4.w}, lb[4] = {lb4.x, lb4.y, lb4.z, lb4.w};
;   float s = y[0] + y[1] + y[2] + y[3];
;   s = rowsum16(s);
;   const float mu = s * (1.f / 64.f);
;   float q = 0.f, bn = 0.f;
; #pragma unroll
;   for (int j = 0; j < 4; ++j) { const float d = y[j] - mu; q += d * d; bn += rr[j] * km[j] * rk[j]; }
;   q = rowsum16(q); bn = rowsum16(bn);
;   const float rstd = rsqrtf(q * (1.f / 64.f) + 64e-5f);
;   float ov[4];
; #pragma unroll
;   for (int j = 0; j < 4; ++j) ov[j] = ((y[j] - mu) * rstd * lw[j] + lb[j] + bn * vv[j]) * gg[j];
;   u16* orw = (u16*)(p.ws + OFF_R3 + SA_KKN * SZ_TOK256 + (size_t)NT * 512 * 2);
;   *(uint2*)(orw + o) = make_uint2(pack2(ov[0], ov[1]), pack2(ov[2], ov[3]));
; }
; DI void phase_readout(const Params& p, int l, int Mout) {
;   LAUNDER_IDS
;   const int wave = tid__ >> 6;
;   for (int r = blk__ * 4 + wave; r < Mout; r += gridDim.x * 4) readout_row(p, l, r);
; }
.LBB0_492:
	s_or_b64 exec, exec, s[4:5]
	v_mov_b32_e32 v0, v163
	s_mov_b32 s4, s2
	v_ashrrev_i32_e32 v0, 6, v0
	v_readlane_b32 s9, v253, 48
	v_lshl_add_u32 v2, s4, 2, v0
	s_nop 0
	v_cmp_gt_i32_e32 vcc, s9, v2
	s_and_saveexec_b64 s[4:5], vcc
	v_readlane_b32 s10, v253, 62
	v_readlane_b32 s12, v254, 0
	v_readlane_b32 s14, v254, 2
	v_readlane_b32 s18, v254, 4
	v_readlane_b32 s20, v254, 6
	v_readlane_b32 s28, v254, 8
	v_readlane_b32 s34, v254, 10
	v_readlane_b32 s11, v253, 63
	v_readlane_b32 s13, v254, 1
	v_readlane_b32 s15, v254, 3
	v_readlane_b32 s19, v254, 5
	v_readlane_b32 s21, v254, 7
	v_readlane_b32 s29, v254, 9
	v_readlane_b32 s35, v254, 11
	s_cbranch_execz .LBB0_495
	s_mov_b64 s[16:17], s[92:93]
	v_mov_b32_e32 v0, v163
	v_lshlrev_b32_e32 v0, 2, v0
	v_and_b32_e32 v0, 0xfc, v0
	v_lshlrev_b32_e32 v3, 2, v0
	global_load_dwordx4 v[40:43], v3, s[18:19]
	global_load_dwordx4 v[44:47], v3, s[20:21]
	global_load_dwordx4 v[48:51], v3, s[28:29]
	v_lshlrev_b32_e32 v52, 1, v0
	v_readfirstlane_b32 s6, v2
	s_lshl_b32 s8, s40, 9
	v_lshl_or_b32 v53, v2, 9, v52
	global_load_dwordx2 v[54:55], v53, s[12:13]
	global_load_dwordx2 v[56:57], v53, s[14:15]
	global_load_dwordx2 v[58:59], v53, s[24:25]
	global_load_dwordx2 v[60:61], v53, s[10:11]
	global_load_dwordx2 v[62:63], v53, s[22:23]
	global_load_dwordx2 v[64:65], v53, s[26:27]
	global_load_dwordx2 v[66:67], v53, s[16:17]
.Lro_loop:
	s_add_i32 s7, s6, s40
	s_cmp_lt_i32 s7, s9
	s_cbranch_scc0 .Lro_last_a
	v_add_u32_e32 v69, s8, v53
	global_load_dwordx2 v[70:71], v69, s[12:13]
	global_load_dwordx2 v[72:73], v69, s[14:15]
	global_load_dwordx2 v[74:75], v69, s[24:25]
	global_load_dwordx2 v[76:77], v69, s[10:11]
	global_load_dwordx2 v[78:79], v69, s[22:23]
	global_load_dwordx2 v[80:81], v69, s[26:27]
	global_load_dwordx2 v[82:83], v69, s[16:17]
	s_waitcnt vmcnt(7)
	v_lshlrev_b32_e32 v4, 16, v54
	v_and_b32_e32 v5, 0xffff0000, v54
	v_lshlrev_b32_e32 v6, 16, v55
	v_and_b32_e32 v7, 0xffff0000, v55
	v_lshlrev_b32_e32 v8, 16, v56
	v_and_b32_e32 v9, 0xffff0000, v56
	v_lshlrev_b32_e32 v10, 16, v57
	v_and_b32_e32 v11, 0xffff0000, v57
	v_pk_add_f32 v[4:5], v[4:5], v[8:9]
	v_pk_add_f32 v[6:7], v[6:7], v[10:11]
	v_lshlrev_b32_e32 v8, 16, v62
	v_and_b32_e32 v9, 0xffff0000, v62
	v_lshlrev_b32_e32 v10, 16, v63
	v_and_b32_e32 v11, 0xffff0000, v63
	v_pk_mul_f32 v[4:5], v[4:5], 0.5 op_sel_hi:[1,0]
	v_pk_mul_f32 v[6:7], v[6:7], 0.5 op_sel_hi:[1,0]
	v_pk_mul_f32 v[4:5], v[4:5], v[8:9]
	v_pk_mul_f32 v[6:7], v[6:7], v[10:11]
	v_pk_mul_f32 v[4:5], v[4:5], v[40:41]
	v_pk_mul_f32 v[6:7], v[6:7], v[42:43]
	v_lshlrev_b32_e32 v12, 16, v58
	v_and_b32_e32 v13, 0xffff0000, v58
	v_lshlrev_b32_e32 v14, 16, v59
	v_and_b32_e32 v15, 0xffff0000, v59
	v_lshlrev_b32_e32 v16, 16, v60
	v_and_b32_e32 v17, 0xffff0000, v60
	v_lshlrev_b32_e32 v18, 16, v61
	v_and_b32_e32 v19, 0xffff0000, v61
	v_add_f32_e32 v0, 0, v4
	v_add_f32_e32 v0, v5, v0
	v_add_f32_e32 v0, v6, v0
	v_add_f32_e32 v0, v7, v0
	v_pk_add_f32 v[22:23], v[12:13], v[16:17]
	v_pk_add_f32 v[26:27], v[14:15], v[18:19]
	v_add_f32_e32 v3, v22, v23
	v_add_f32_e32 v3, v3, v26
	v_add_f32_e32 v3, v27, v3
	s_nop 0
	v_add_f32_dpp v0, v0, v0 row_ror:8 row_mask:0xf bank_mask:0xf bound_ctrl:1
	s_nop 0
	v_add_f32_dpp v3, v3, v3 row_ror:8 row_mask:0xf bank_mask:0xf bound_ctrl:1
	v_add_f32_dpp v0, v0, v0 row_ror:4 row_mask:0xf bank_mask:0xf bound_ctrl:1
	s_nop 0
	v_add_f32_dpp v3, v3, v3 row_ror:4 row_mask:0xf bank_mask:0xf bound_ctrl:1
	v_add_f32_dpp v0, v0, v0 row_ror:2 row_mask:0xf bank_mask:0xf bound_ctrl:1
	s_nop 0
	v_add_f32_dpp v3, v3, v3 row_ror:2 row_mask:0xf bank_mask:0xf bound_ctrl:1
	v_add_f32_dpp v0, v0, v0 row_ror:1 row_mask:0xf bank_mask:0xf bound_ctrl:1
	s_nop 0
	v_add_f32_dpp v3, v3, v3 row_ror:1 row_mask:0xf bank_mask:0xf bound_ctrl:1
	v_mul_f32_e32 v24, 0x3c800000, v3
	v_pk_add_f32 v[22:23], v[22:23], v[24:25] op_sel_hi:[1,0] neg_lo:[0,1] neg_hi:[0,1]
	v_pk_add_f32 v[24:25], v[26:27], v[24:25] op_sel_hi:[1,0] neg_lo:[0,1] neg_hi:[0,1]
	v_pk_mul_f32 v[28:29], v[22:23], v[22:23]
	v_pk_mul_f32 v[26:27], v[24:25], v[24:25]
	v_add_f32_e32 v3, v28, v29
	v_add_f32_e32 v3, v26, v3
	v_add_f32_e32 v3, v27, v3
	v_mov_b32_e32 v26, 0x3a27c5ac
	s_nop 0
	v_add_f32_dpp v3, v3, v3 row_ror:8 row_mask:0xf bank_mask:0xf bound_ctrl:1
	s_nop 1
	v_add_f32_dpp v3, v3, v3 row_ror:4 row_mask:0xf bank_mask:0xf bound_ctrl:1
	s_nop 1
	v_add_f32_dpp v3, v3, v3 row_ror:2 row_mask:0xf bank_mask:0xf bound_ctrl:1
	s_nop 1
	v_add_f32_dpp v3, v3, v3 row_ror:1 row_mask:0xf bank_mask:0xf bound_ctrl:1
	v_fmamk_f32 v3, v3, 0x3c800000, v26
	v_cmp_gt_f32_e32 vcc, s31, v3
	v_mul_f32_e32 v26, 0x4b800000, v3
	s_nop 0
	v_cndmask_b32_e32 v3, v3, v26, vcc
	v_rsq_f32_e32 v3, v3
	s_nop 0
	v_mul_f32_e32 v26, 0x45800000, v3
	v_cndmask_b32_e32 v26, v3, v26, vcc
	v_pk_mul_f32 v[22:23], v[22:23], v[26:27] op_sel_hi:[1,0]
	v_lshlrev_b32_e32 v8, 16, v64
	v_and_b32_e32 v9, 0xffff0000, v64
	v_lshlrev_b32_e32 v6, 16, v65
	v_and_b32_e32 v7, 0xffff0000, v65
	v_lshlrev_b32_e32 v12, 16, v66
	v_and_b32_e32 v13, 0xffff0000, v66
	v_lshlrev_b32_e32 v10, 16, v67
	v_and_b32_e32 v11, 0xffff0000, v67
	v_pk_fma_f32 v[14:15], v[44:45], v[22:23], v[48:49]
	s_nop 0
	v_pk_fma_f32 v[8:9], v[0:1], v[8:9], v[14:15] op_sel_hi:[0,1,1]
	v_pk_mul_f32 v[8:9], v[8:9], v[12:13]
	v_pk_mul_f32 v[12:13], v[24:25], v[26:27] op_sel_hi:[1,0]
	v_cvt_pk_bf16_f32 v8, v8, v9
	v_pk_fma_f32 v[12:13], v[46:47], v[12:13], v[50:51]
	s_nop 0
	v_pk_fma_f32 v[6:7], v[0:1], v[6:7], v[12:13] op_sel_hi:[0,1,1]
	v_pk_mul_f32 v[6:7], v[6:7], v[10:11]
	s_nop 0
	v_cvt_pk_bf16_f32 v9, v6, v7
	global_store_dwordx2 v53, v[8:9], s[34:35]
	s_mov_b32 s6, s7
	s_add_i32 s7, s6, s40
	s_cmp_lt_i32 s7, s9
	s_cbranch_scc0 .Lro_last_b
; DI float bflo(unsigned u) { return __uint_as_float(u << 16); }
; DI float bfhi(unsigned u) { return __uint_as_float(u & 0xffff0000u); }
; DI unsigned pack2(float a, float b) { float2_t v = {a, b}; bf16x2_t r = __builtin_convertvector(v, bf16x2_t); return __builtin_bit_cast(unsigned, r); }
; DI void readout_row(const Params& p, int l, int r) {
;     ...
;   const size_t o = (size_t)r * 256 + lane * 4;
;   const u16* Yf = (const u16*)(p.ws + OFF_R2);
;   const uint2 yf = *(const uint2*)(Yf + o), yb = *(const uint2*)(Yf + AS + o);
;   const uint2 ur = *(const uint2*)(sc + SA_R * AS + o), uv = *(const uint2*)(sc + SA_V * AS + o);
;   const uint2 kf = *(const uint2*)(sc + SA_KDF * AS + o), kb = *(const uint2*)(sc + SA_KDB * AS + o), ug = *(const uint2*)(sc + SA_G * AS + o);
;   float y[4] = {bflo(yf.x) + bflo(yb.x), bfhi(yf.x) + bfhi(yb.x), bflo(yf.y) + bflo(yb.y), bfhi(yf.y) + bfhi(yb.y)};
;   const float rr[4] = {bflo(ur.x), bfhi(ur.x), bflo(ur.y), bfhi(ur.y)};
;   const float vv[4] = {bflo(uv.x), bfhi(uv.x), bflo(uv.y), bfhi(uv.y)};
;   const float km[4] = {0.5f * (bflo(kf.x) + bflo(kb.x)), 0.5f * (bfhi(kf.x) + bfhi(kb.x)), 0.5f * (bflo(kf.y) + bflo(kb.y)), 0.5f * (bfhi(kf.y) + bfhi(kb.y))};
;   const float gg[4] = {bflo(ug.x), bfhi(ug.x), bflo(ug.y), bfhi(ug.y)};
;   const float4 rk4 = *(const float4*)(p.in[I_RK] + l * 256 + lane * 4);
;   const float4 lw4 = *(const float4*)(p.in[I_LNW] + l * 256 + lane * 4);
;   const float4 lb4 = *(const float4*)(p.in[I_LNB] + l * 256 + lane * 4);
;   const float rk[4] = {rk4.x, rk4.y, rk4.z, rk4.w}, lw[4] = {lw4.x, lw4.y, lw4.z, lw4.w}, lb[4] = {lb4.x, lb4.y, lb4.z, lb4.w};
;   float s = y[0] + y[1] + y[2] + y[3];
;   s = rowsum16(s);
;   const float mu = s * (1.f / 64.f);
;   float q = 0.f, bn = 0.f;
; #pragma unroll
;   for (int j = 0; j < 4; ++j) { const float d = y[j] - mu; q += d * d; bn += rr[j] * km[j] * rk[j]; }
;   q = rowsum16(q); bn = rowsum16(bn);
;   const float rstd = rsqrtf(q * (1.f / 64.f) + 64e-5f);
;   float ov[4];
; #pragma unroll
;   for (int j = 0; j < 4; ++j) ov[j] = ((y[j] - mu) * rstd * lw[j] + lb[j] + bn * vv[j]) * gg[j];
;   u16* orw = (u16*)(p.ws + OFF_R3 + SA_KKN * SZ_TOK256 + (size_t)NT * 512 * 2);
;   *(uint2*)(orw + o) = make_uint2(pack2(ov[0], ov[1]), pack2(ov[2], ov[3]));
; }
	v_add_u32_e32 v53, s8, v69
	global_load_dwordx2 v[54:55], v53, s[12:13]
	global_load_dwordx2 v[56:57], v53, s[14:15]
	global_load_dwordx2 v[58:59], v53, s[24:25]
	global_load_dwordx2 v[60:61], v53, s[10:11]
	global_load_dwordx2 v[62:63], v53, s[22:23]
	global_load_dwordx2 v[64:65], v53, s[26:27]
	global_load_dwordx2 v[66:67], v53, s[16:17]
	s_waitcnt vmcnt(7)
	v_lshlrev_b32_e32 v4, 16, v70
	v_and_b32_e32 v5, 0xffff0000, v70
	v_lshlrev_b32_e32 v6, 16, v71
	v_and_b32_e32 v7, 0xffff0000, v71
	v_lshlrev_b32_e32 v8, 16, v72
	v_and_b32_e32 v9, 0xffff0000, v72
	v_lshlrev_b32_e32 v10, 16, v73
	v_and_b32_e32 v11, 0xffff0000, v73
	v_pk_add_f32 v[4:5], v[4:5], v[8:9]
	v_pk_add_f32 v[6:7], v[6:7], v[10:11]
	v_lshlrev_b32_e32 v8, 16, v78
	v_and_b32_e32 v9, 0xffff0000, v78
	v_lshlrev_b32_e32 v10, 16, v79
	v_and_b32_e32 v11, 0xffff0000, v79
	v_pk_mul_f32 v[4:5], v[4:5], 0.5 op_sel_hi:[1,0]
	v_pk_mul_f32 v[6:7], v[6:7], 0.5 op_sel_hi:[1,0]
	v_pk_mul_f32 v[4:5], v[4:5], v[8:9]
	v_pk_mul_f32 v[6:7], v[6:7], v[10:11]
	v_pk_mul_f32 v[4:5], v[4:5], v[40:41]
	v_pk_mul_f32 v[6:7], v[6:7], v[42:43]
	v_lshlrev_b32_e32 v12, 16, v74
	v_and_b32_e32 v13, 0xffff0000, v74
	v_lshlrev_b32_e32 v14, 16, v75
	v_and_b32_e32 v15, 0xffff0000, v75
	v_lshlrev_b32_e32 v16, 16, v76
	v_and_b32_e32 v17, 0xffff0000, v76
	v_lshlrev_b32_e32 v18, 16, v77
	v_and_b32_e32 v19, 0xffff0000, v77
	v_add_f32_e32 v0, 0, v4
	v_add_f32_e32 v0, v5, v0
	v_add_f32_e32 v0, v6, v0
	v_add_f32_e32 v0, v7, v0
	v_pk_add_f32 v[22:23], v[12:13], v[16:17]
	v_pk_add_f32 v[26:27], v[14:15], v[18:19]
	v_add_f32_e32 v3, v22, v23
	v_add_f32_e32 v3, v3, v26
	v_add_f32_e32 v3, v27, v3
	s_nop 0
	v_add_f32_dpp v0, v0, v0 row_ror:8 row_mask:0xf bank_mask:0xf bound_ctrl:1
	s_nop 0
	v_add_f32_dpp v3, v3, v3 row_ror:8 row_mask:0xf bank_mask:0xf bound_ctrl:1
	v_add_f32_dpp v0, v0, v0 row_ror:4 row_mask:0xf bank_mask:0xf bound_ctrl:1
	s_nop 0
	v_add_f32_dpp v3, v3, v3 row_ror:4 row_mask:0xf bank_mask:0xf bound_ctrl:1
	v_add_f32_dpp v0, v0, v0 row_ror:2 row_mask:0xf bank_mask:0xf bound_ctrl:1
	s_nop 0
	v_add_f32_dpp v3, v3, v3 row_ror:2 row_mask:0xf bank_mask:0xf bound_ctrl:1
	v_add_f32_dpp v0, v0, v0 row_ror:1 row_mask:0xf bank_mask:0xf bound_ctrl:1
	s_nop 0
	v_add_f32_dpp v3, v3, v3 row_ror:1 row_mask:0xf bank_mask:0xf bound_ctrl:1
	v_mul_f32_e32 v24, 0x3c800000, v3
	v_pk_add_f32 v[22:23], v[22:23], v[24:25] op_sel_hi:[1,0] neg_lo:[0,1] neg_hi:[0,1]
	v_pk_add_f32 v[24:25], v[26:27], v[24:25] op_sel_hi:[1,0] neg_lo:[0,1] neg_hi:[0,1]
	v_pk_mul_f32 v[28:29], v[22:23], v[22:23]
	v_pk_mul_f32 v[26:27], v[24:25], v[24:25]
	v_add_f32_e32 v3, v28, v29
	v_add_f32_e32 v3, v26, v3
	v_add_f32_e32 v3, v27, v3
	v_mov_b32_e32 v26, 0x3a27c5ac
	s_nop 0
	v_add_f32_dpp v3, v3, v3 row_ror:8 row_mask:0xf bank_mask:0xf bound_ctrl:1
	s_nop 1
	v_add_f32_dpp v3, v3, v3 row_ror:4 row_mask:0xf bank_mask:0xf bound_ctrl:1
	s_nop 1
	v_add_f32_dpp v3, v3, v3 row_ror:2 row_mask:0xf bank_mask:0xf bound_ctrl:1
	s_nop 1
	v_add_f32_dpp v3, v3, v3 row_ror:1 row_mask:0xf bank_mask:0xf bound_ctrl:1
	v_fmamk_f32 v3, v3, 0x3c800000, v26
	v_cmp_gt_f32_e32 vcc, s31, v3
	v_mul_f32_e32 v26, 0x4b800000, v3
	s_nop 0
	v_cndmask_b32_e32 v3, v3, v26, vcc
	v_rsq_f32_e32 v3, v3
	s_nop 0
	v_mul_f32_e32 v26, 0x45800000, v3
	v_cndmask_b32_e32 v26, v3, v26, vcc
	v_pk_mul_f32 v[22:23], v[22:23], v[26:27] op_sel_hi:[1,0]
	v_lshlrev_b32_e32 v8, 16, v80
	v_and_b32_e32 v9, 0xffff0000, v80
	v_lshlrev_b32_e32 v6, 16, v81
	v_and_b32_e32 v7, 0xffff0000, v81
	v_lshlrev_b32_e32 v12, 16, v82
	v_and_b32_e32 v13, 0xffff0000, v82
	v_lshlrev_b32_e32 v10, 16, v83
	v_and_b32_e32 v11, 0xffff0000, v83
	v_pk_fma_f32 v[14:15], v[44:45], v[22:23], v[48:49]
	s_nop 0
	v_pk_fma_f32 v[8:9], v[0:1], v[8:9], v[14:15] op_sel_hi:[0,1,1]
	v_pk_mul_f32 v[8:9], v[8:9], v[12:13]
	v_pk_mul_f32 v[12:13], v[24:25], v[26:27] op_sel_hi:[1,0]
	v_cvt_pk_bf16_f32 v8, v8, v9
	v_pk_fma_f32 v[12:13], v[46:47], v[12:13], v[50:51]
	s_nop 0
	v_pk_fma_f32 v[6:7], v[0:1], v[6:7], v[12:13] op_sel_hi:[0,1,1]
	v_pk_mul_f32 v[6:7], v[6:7], v[10:11]
	s_nop 0
	v_cvt_pk_bf16_f32 v9, v6, v7
	global_store_dwordx2 v69, v[8:9], s[34:35]
	s_mov_b32 s6, s7
	s_branch .Lro_loop
.Lro_last_a:
	s_waitcnt vmcnt(0)
	v_lshlrev_b32_e32 v4, 16, v54
	v_and_b32_e32 v5, 0xffff0000, v54
	v_lshlrev_b32_e32 v6, 16, v55
	v_and_b32_e32 v7, 0xffff0000, v55
	v_lshlrev_b32_e32 v8, 16, v56
	v_and_b32_e32 v9, 0xffff0000, v56
	v_lshlrev_b32_e32 v10, 16, v57
	v_and_b32_e32 v11, 0xffff0000, v57
	v_pk_add_f32 v[4:5], v[4:5], v[8:9]
	v_pk_add_f32 v[6:7], v[6:7], v[10:11]
	v_lshlrev_b32_e32 v8, 16, v62
	v_and_b32_e32 v9, 0xffff0000, v62
	v_lshlrev_b32_e32 v10, 16, v63
	v_and_b32_e32 v11, 0xffff0000, v63
	v_pk_mul_f32 v[4:5], v[4:5], 0.5 op_sel_hi:[1,0]
	v_pk_mul_f32 v[6:7], v[6:7], 0.5 op_sel_hi:[1,0]
	v_pk_mul_f32 v[4:5], v[4:5], v[8:9]
	v_pk_mul_f32 v[6:7], v[6:7], v[10:11]
	v_pk_mul_f32 v[4:5], v[4:5], v[40:41]
	v_pk_mul_f32 v[6:7], v[6:7], v[42:43]
	v_lshlrev_b32_e32 v12, 16, v58
	v_and_b32_e32 v13, 0xffff0000, v58
	v_lshlrev_b32_e32 v14, 16, v59
	v_and_b32_e32 v15, 0xffff0000, v59
	v_lshlrev_b32_e32 v16, 16, v60
	v_and_b32_e32 v17, 0xffff0000, v60
	v_lshlrev_b32_e32 v18, 16, v61
	v_and_b32_e32 v19, 0xffff0000, v61
	v_add_f32_e32 v0, 0, v4
	v_add_f32_e32 v0, v5, v0
	v_add_f32_e32 v0, v6, v0
	v_add_f32_e32 v0, v7, v0
	v_pk_add_f32 v[22:23], v[12:13], v[16:17]
	v_pk_add_f32 v[26:27], v[14:15], v[18:19]
	v_add_f32_e32 v3, v22, v23
	v_add_f32_e32 v3, v3, v26
	v_add_f32_e32 v3, v27, v3
	s_nop 0
	v_add_f32_dpp v0, v0, v0 row_ror:8 row_mask:0xf bank_mask:0xf bound_ctrl:1
	s_nop 0
	v_add_f32_dpp v3, v3, v3 row_ror:8 row_mask:0xf bank_mask:0xf bound_ctrl:1
; DI float bflo(unsigned u) { return __uint_as_float(u << 16); }
; DI float bfhi(unsigned u) { return __uint_as_float(u & 0xffff0000u); }
; DI unsigned pack2(float a, float b) { float2_t v = {a, b}; bf16x2_t r = __builtin_convertvector(v, bf16x2_t); return __builtin_bit_cast(unsigned, r); }
; DI void readout_row(const Params& p, int l, int r) {
;     ...
;   const size_t o = (size_t)r * 256 + lane * 4;
;   const u16* Yf = (const u16*)(p.ws + OFF_R2);
;   const uint2 yf = *(const uint2*)(Yf + o), yb = *(const uint2*)(Yf + AS + o);
;   const uint2 ur = *(const uint2*)(sc + SA_R * AS + o), uv = *(const uint2*)(sc + SA_V * AS + o);
;   const uint2 kf = *(const uint2*)(sc + SA_KDF * AS + o), kb = *(const uint2*)(sc + SA_KDB * AS + o), ug = *(const uint2*)(sc + SA_G * AS + o);
;   float y[4] = {bflo(yf.x) + bflo(yb.x), bfhi(yf.x) + bfhi(yb.x), bflo(yf.y) + bflo(yb.y), bfhi(yf.y) + bfhi(yb.y)};
;   const float rr[4] = {bflo(ur.x), bfhi(ur.x), bflo(ur.y), bfhi(ur.y)};
;   const float vv[4] = {bflo(uv.x), bfhi(uv.x), bflo(uv.y), bfhi(uv.y)};
;   const float km[4] = {0.5f * (bflo(kf.x) + bflo(kb.x)), 0.5f * (bfhi(kf.x) + bfhi(kb.x)), 0.5f * (bflo(kf.y) + bflo(kb.y)), 0.5f * (bfhi(kf.y) + bfhi(kb.y))};
;   const float gg[4] = {bflo(ug.x), bfhi(ug.x), bflo(ug.y), bfhi(ug.y)};
;   const float4 rk4 = *(const float4*)(p.in[I_RK] + l * 256 + lane * 4);
;   const float4 lw4 = *(const float4*)(p.in[I_LNW] + l * 256 + lane * 4);
;   const float4 lb4 = *(const float4*)(p.in[I_LNB] + l * 256 + lane * 4);
;   const float rk[4] = {rk4.x, rk4.y, rk4.z, rk4.w}, lw[4] = {lw4.x, lw4.y, lw4.z, lw4.w}, lb[4] = {lb4.x, lb4.y, lb4.z, lb4.w};
;   float s = y[0] + y[1] + y[2] + y[3];
;   s = rowsum16(s);
;   const float mu = s * (1.f / 64.f);
;   float q = 0.f, bn = 0.f;
; #pragma unroll
;   for (int j = 0; j < 4; ++j) { const float d = y[j] - mu; q += d * d; bn += rr[j] * km[j] * rk[j]; }
;   q = rowsum16(q); bn = rowsum16(bn);
;   const float rstd = rsqrtf(q * (1.f / 64.f) + 64e-5f);
;   float ov[4];
; #pragma unroll
;   for (int j = 0; j < 4; ++j) ov[j] = ((y[j] - mu) * rstd * lw[j] + lb[j] + bn * vv[j]) * gg[j];
;   u16* orw = (u16*)(p.ws + OFF_R3 + SA_KKN * SZ_TOK256 + (size_t)NT * 512 * 2);
;   *(uint2*)(orw + o) = make_uint2(pack2(ov[0], ov[1]), pack2(ov[2], ov[3]));
; }
	v_add_f32_dpp v0, v0, v0 row_ror:4 row_mask:0xf bank_mask:0xf bound_ctrl:1
	s_nop 0
	v_add_f32_dpp v3, v3, v3 row_ror:4 row_mask:0xf bank_mask:0xf bound_ctrl:1
	v_add_f32_dpp v0, v0, v0 row_ror:2 row_mask:0xf bank_mask:0xf bound_ctrl:1
	s_nop 0
	v_add_f32_dpp v3, v3, v3 row_ror:2 row_mask:0xf bank_mask:0xf bound_ctrl:1
	v_add_f32_dpp v0, v0, v0 row_ror:1 row_mask:0xf bank_mask:0xf bound_ctrl:1
	s_nop 0
	v_add_f32_dpp v3, v3, v3 row_ror:1 row_mask:0xf bank_mask:0xf bound_ctrl:1
	v_mul_f32_e32 v24, 0x3c800000, v3
	v_pk_add_f32 v[22:23], v[22:23], v[24:25] op_sel_hi:[1,0] neg_lo:[0,1] neg_hi:[0,1]
	v_pk_add_f32 v[24:25], v[26:27], v[24:25] op_sel_hi:[1,0] neg_lo:[0,1] neg_hi:[0,1]
	v_pk_mul_f32 v[28:29], v[22:23], v[22:23]
	v_pk_mul_f32 v[26:27], v[24:25], v[24:25]
	v_add_f32_e32 v3, v28, v29
	v_add_f32_e32 v3, v26, v3
	v_add_f32_e32 v3, v27, v3
	v_mov_b32_e32 v26, 0x3a27c5ac
	s_nop 0
	v_add_f32_dpp v3, v3, v3 row_ror:8 row_mask:0xf bank_mask:0xf bound_ctrl:1
	s_nop 1
	v_add_f32_dpp v3, v3, v3 row_ror:4 row_mask:0xf bank_mask:0xf bound_ctrl:1
	s_nop 1
	v_add_f32_dpp v3, v3, v3 row_ror:2 row_mask:0xf bank_mask:0xf bound_ctrl:1
	s_nop 1
	v_add_f32_dpp v3, v3, v3 row_ror:1 row_mask:0xf bank_mask:0xf bound_ctrl:1
	v_fmamk_f32 v3, v3, 0x3c800000, v26
	v_cmp_gt_f32_e32 vcc, s31, v3
	v_mul_f32_e32 v26, 0x4b800000, v3
	s_nop 0
	v_cndmask_b32_e32 v3, v3, v26, vcc
	v_rsq_f32_e32 v3, v3
	s_nop 0
	v_mul_f32_e32 v26, 0x45800000, v3
	v_cndmask_b32_e32 v26, v3, v26, vcc
	v_pk_mul_f32 v[22:23], v[22:23], v[26:27] op_sel_hi:[1,0]
	v_lshlrev_b32_e32 v8, 16, v64
	v_and_b32_e32 v9, 0xffff0000, v64
	v_lshlrev_b32_e32 v6, 16, v65
	v_and_b32_e32 v7, 0xffff0000, v65
	v_lshlrev_b32_e32 v12, 16, v66
	v_and_b32_e32 v13, 0xffff0000, v66
	v_lshlrev_b32_e32 v10, 16, v67
	v_and_b32_e32 v11, 0xffff0000, v67
	v_pk_fma_f32 v[14:15], v[44:45], v[22:23], v[48:49]
	s_nop 0
	v_pk_fma_f32 v[8:9], v[0:1], v[8:9], v[14:15] op_sel_hi:[0,1,1]
	v_pk_mul_f32 v[8:9], v[8:9], v[12:13]
	v_pk_mul_f32 v[12:13], v[24:25], v[26:27] op_sel_hi:[1,0]
	v_cvt_pk_bf16_f32 v8, v8, v9
	v_pk_fma_f32 v[12:13], v[46:47], v[12:13], v[50:51]
	s_nop 0
	v_pk_fma_f32 v[6:7], v[0:1], v[6:7], v[12:13] op_sel_hi:[0,1,1]
	v_pk_mul_f32 v[6:7], v[6:7], v[10:11]
	s_nop 0
	v_cvt_pk_bf16_f32 v9, v6, v7
	global_store_dwordx2 v53, v[8:9], s[34:35]
	s_branch .Lro_done
.Lro_last_b:
	s_waitcnt vmcnt(0)
	v_lshlrev_b32_e32 v4, 16, v70
	v_and_b32_e32 v5, 0xffff0000, v70
	v_lshlrev_b32_e32 v6, 16, v71
	v_and_b32_e32 v7, 0xffff0000, v71
	v_lshlrev_b32_e32 v8, 16, v72
	v_and_b32_e32 v9, 0xffff0000, v72
	v_lshlrev_b32_e32 v10, 16, v73
	v_and_b32_e32 v11, 0xffff0000, v73
	v_pk_add_f32 v[4:5], v[4:5], v[8:9]
	v_pk_add_f32 v[6:7], v[6:7], v[10:11]
	v_lshlrev_b32_e32 v8, 16, v78
	v_and_b32_e32 v9, 0xffff0000, v78
	v_lshlrev_b32_e32 v10, 16, v79
	v_and_b32_e32 v11, 0xffff0000, v79
	v_pk_mul_f32 v[4:5], v[4:5], 0.5 op_sel_hi:[1,0]
	v_pk_mul_f32 v[6:7], v[6:7], 0.5 op_sel_hi:[1,0]
	v_pk_mul_f32 v[4:5], v[4:5], v[8:9]
	v_pk_mul_f32 v[6:7], v[6:7], v[10:11]
	v_pk_mul_f32 v[4:5], v[4:5], v[40:41]
	v_pk_mul_f32 v[6:7], v[6:7], v[42:43]
	v_lshlrev_b32_e32 v12, 16, v74
	v_and_b32_e32 v13, 0xffff0000, v74
	v_lshlrev_b32_e32 v14, 16, v75
	v_and_b32_e32 v15, 0xffff0000, v75
	v_lshlrev_b32_e32 v16, 16, v76
	v_and_b32_e32 v17, 0xffff0000, v76
	v_lshlrev_b32_e32 v18, 16, v77
	v_and_b32_e32 v19, 0xffff0000, v77
	v_add_f32_e32 v0, 0, v4
	v_add_f32_e32 v0, v5, v0
	v_add_f32_e32 v0, v6, v0
	v_add_f32_e32 v0, v7, v0
	v_pk_add_f32 v[22:23], v[12:13], v[16:17]
	v_pk_add_f32 v[26:27], v[14:15], v[18:19]
	v_add_f32_e32 v3, v22, v23
	v_add_f32_e32 v3, v3, v26
	v_add_f32_e32 v3, v27, v3
	s_nop 0
	v_add_f32_dpp v0, v0, v0 row_ror:8 row_mask:0xf bank_mask:0xf bound_ctrl:1
	s_nop 0
	v_add_f32_dpp v3, v3, v3 row_ror:8 row_mask:0xf bank_mask:0xf bound_ctrl:1
	v_add_f32_dpp v0, v0, v0 row_ror:4 row_mask:0xf bank_mask:0xf bound_ctrl:1
	s_nop 0
	v_add_f32_dpp v3, v3, v3 row_ror:4 row_mask:0xf bank_mask:0xf bound_ctrl:1
	v_add_f32_dpp v0, v0, v0 row_ror:2 row_mask:0xf bank_mask:0xf bound_ctrl:1
	s_nop 0
	v_add_f32_dpp v3, v3, v3 row_ror:2 row_mask:0xf bank_mask:0xf bound_ctrl:1
	v_add_f32_dpp v0, v0, v0 row_ror:1 row_mask:0xf bank_mask:0xf bound_ctrl:1
	s_nop 0
	v_add_f32_dpp v3, v3, v3 row_ror:1 row_mask:0xf bank_mask:0xf bound_ctrl:1
	v_mul_f32_e32 v24, 0x3c800000, v3
	v_pk_add_f32 v[22:23], v[22:23], v[24:25] op_sel_hi:[1,0] neg_lo:[0,1] neg_hi:[0,1]
	v_pk_add_f32 v[24:25], v[26:27], v[24:25] op_sel_hi:[1,0] neg_lo:[0,1] neg_hi:[0,1]
	v_pk_mul_f32 v[28:29], v[22:23], v[22:23]
	v_pk_mul_f32 v[26:27], v[24:25], v[24:25]
	v_add_f32_e32 v3, v28, v29
	v_add_f32_e32 v3, v26, v3
	v_add_f32_e32 v3, v27, v3
	v_mov_b32_e32 v26, 0x3a27c5ac
	s_nop 0
	v_add_f32_dpp v3, v3, v3 row_ror:8 row_mask:0xf bank_mask:0xf bound_ctrl:1
	s_nop 1
	v_add_f32_dpp v3, v3, v3 row_ror:4 row_mask:0xf bank_mask:0xf bound_ctrl:1
	s_nop 1
	v_add_f32_dpp v3, v3, v3 row_ror:2 row_mask:0xf bank_mask:0xf bound_ctrl:1
	s_nop 1
	v_add_f32_dpp v3, v3, v3 row_ror:1 row_mask:0xf bank_mask:0xf bound_ctrl:1
	v_fmamk_f32 v3, v3, 0x3c800000, v26
	v_cmp_gt_f32_e32 vcc, s31, v3
	v_mul_f32_e32 v26, 0x4b800000, v3
	s_nop 0
	v_cndmask_b32_e32 v3, v3, v26, vcc
	v_rsq_f32_e32 v3, v3
	s_nop 0
	v_mul_f32_e32 v26, 0x45800000, v3
	v_cndmask_b32_e32 v26, v3, v26, vcc
	v_pk_mul_f32 v[22:23], v[22:23], v[26:27] op_sel_hi:[1,0]
	v_lshlrev_b32_e32 v8, 16, v80
	v_and_b32_e32 v9, 0xffff0000, v80
	v_lshlrev_b32_e32 v6, 16, v81
	v_and_b32_e32 v7, 0xffff0000, v81
	v_lshlrev_b32_e32 v12, 16, v82
	v_and_b32_e32 v13, 0xffff0000, v82
	v_lshlrev_b32_e32 v10, 16, v83
	v_and_b32_e32 v11, 0xffff0000, v83
	v_pk_fma_f32 v[14:15], v[44:45], v[22:23], v[48:49]
	s_nop 0
	v_pk_fma_f32 v[8:9], v[0:1], v[8:9], v[14:15] op_sel_hi:[0,1,1]
	v_pk_mul_f32 v[8:9], v[8:9], v[12:13]
	v_pk_mul_f32 v[12:13], v[24:25], v[26:27] op_sel_hi:[1,0]
	v_cvt_pk_bf16_f32 v8, v8, v9
	v_pk_fma_f32 v[12:13], v[46:47], v[12:13], v[50:51]
	s_nop 0
	v_pk_fma_f32 v[6:7], v[0:1], v[6:7], v[12:13] op_sel_hi:[0,1,1]
	v_pk_mul_f32 v[6:7], v[6:7], v[10:11]
	s_nop 0
	v_cvt_pk_bf16_f32 v9, v6, v7
	global_store_dwordx2 v69, v[8:9], s[34:35]
.Lro_done:
.LBB0_495:
	s_or_b64 exec, exec, s[4:5]
